# unitM output: pairs of 2-byte row stores merged into 4-byte stores (DPP neighbour-column exchange)
# speedup vs baseline: 1.0010x; 1.0010x over previous
; __device__ __forceinline__ unsigned cvtpk(float lo, float hi) { f32x2_t v = {lo, hi}; bf16x2_t b = __builtin_convertvector(v, bf16x2_t); return __builtin_bit_cast(unsigned, b); }
; __device__ __forceinline__ int crowc(int r) { return (r & 3) + 8 * (r >> 2); }
; template <int D, int DV, bool TAB, bool BITS, int KT> ...
;     ...
;     for (int j = 0; j < 4; ++j) { const f32x4 a4 = *(const f32x4*)(wsf + 8 * j + 4 * hi);
; #pragma unroll
;         for (int dt = 0; dt < DV / 32; ++dt) { o[dt][4 * j + 0] *= a4[0]; o[dt][4 * j + 1] *= a4[1]; o[dt][4 * j + 2] *= a4[2]; o[dt][4 * j + 3] *= a4[3]; } }
;     __builtin_amdgcn_fence(__ATOMIC_RELEASE, "wavefront"); __builtin_amdgcn_wave_barrier();
; }
; template <int DV>
; __device__ __forceinline__ void attn_store(const f32x16 (&o)[DV / 32], bf16_t* Op, int ldo) {
;     int tid_o = threadIdx.x; asm volatile("" : "+v"(tid_o));
;     const int lane = tid_o & 63, wid = tid_o >> 6, r32 = lane & 31, hi = lane >> 5;
; #pragma unroll
;     for (int dt = 0; dt < DV / 32; ++dt)
; #pragma unroll
;         for (int r = 0; r < 16; ++r) { const int row = 32 * wid + crowc(r) + 4 * hi; Op[(size_t)row * ldo + dt * 32 + r32] = (bf16_t)(cvtpk(o[dt][r], 0.f) & 0xffffu); }
.LBB0_1185:
	s_or_b64 exec, exec, s[4:5]
	v_add_u32_e32 v0, s70, v0
	ds_read_b128 v[66:69], v0
	ds_read_b128 v[70:73], v0 offset:32
	s_add_u32 s0, s2, s0
	s_addc_u32 s1, s3, s1
	s_lshl_b32 s4, s63, 1
	s_waitcnt lgkmcnt(1)
	v_mul_f32_e32 v50, v50, v66
	v_mul_f32_e32 v51, v51, v67
	v_mul_f32_e32 v52, v52, v68
	v_mul_f32_e32 v53, v53, v69
	v_mul_f32_e32 v74, v34, v66
	v_mul_f32_e32 v75, v35, v67
	v_mul_f32_e32 v36, v36, v68
	v_mul_f32_e32 v37, v37, v69
	v_mul_f32_e32 v76, v18, v66
	v_mul_f32_e32 v77, v19, v67
	v_mul_f32_e32 v78, v20, v68
	v_mul_f32_e32 v79, v21, v69
	v_mul_f32_e32 v66, v2, v66
	v_mul_f32_e32 v67, v3, v67
	v_mul_f32_e32 v68, v4, v68
	v_mul_f32_e32 v69, v5, v69
	ds_read_b128 v[2:5], v0 offset:64
	s_waitcnt lgkmcnt(1)
	v_mul_f32_e32 v18, v54, v70
	v_mul_f32_e32 v19, v55, v71
	v_mul_f32_e32 v20, v56, v72
	v_mul_f32_e32 v21, v57, v73
	v_mul_f32_e32 v38, v38, v70
	v_mul_f32_e32 v39, v39, v71
	v_mul_f32_e32 v40, v40, v72
	v_mul_f32_e32 v41, v41, v73
	v_mul_f32_e32 v54, v22, v70
	v_mul_f32_e32 v55, v23, v71
	v_mul_f32_e32 v56, v24, v72
	v_mul_f32_e32 v57, v25, v73
	v_mul_f32_e32 v70, v6, v70
	v_mul_f32_e32 v71, v7, v71
	v_mul_f32_e32 v72, v8, v72
	v_mul_f32_e32 v73, v9, v73
	ds_read_b128 v[6:9], v0 offset:96
	v_mov_b32_e32 v0, v228
	s_waitcnt lgkmcnt(1)
	v_mul_f32_e32 v23, v58, v2
	v_mul_f32_e32 v42, v42, v2
	v_mul_f32_e32 v58, v26, v2
	v_mul_f32_e32 v80, v10, v2
	s_add_u32 s0, s0, s4
	v_mul_f32_e32 v25, v59, v3
	v_ashrrev_i32_e32 v2, 1, v0
	v_mul_f32_e32 v43, v43, v3
	v_mul_f32_e32 v59, v27, v3
	v_mul_f32_e32 v81, v11, v3
	s_addc_u32 s1, s1, 0
	s_lshl_b32 s4, s72, 1
	v_and_b32_e32 v3, 31, v0
	v_and_b32_e32 v2, 0xffffffe0, v2
	v_lshrrev_b32_e32 v0, 3, v0
	s_add_u32 s0, s0, s4
	v_and_or_b32 v2, v0, 4, v2
	s_waitcnt lgkmcnt(0)
	v_mul_f32_e32 v64, v64, v8
	v_mul_f32_e32 v48, v48, v8
	v_mul_f32_e32 v86, v32, v8
	v_mul_f32_e32 v90, v16, v8
	s_addc_u32 s1, s1, 0
	v_lshlrev_b32_e32 v0, 1, v3
	v_ashrrev_i32_e32 v3, 31, v2
	v_or_b32_e32 v8, 1, v2
	v_mul_f32_e32 v34, v60, v4
	v_mul_f32_e32 v35, v61, v5
	v_mul_f32_e32 v44, v44, v4
	v_mul_f32_e32 v45, v45, v5
	v_mul_f32_e32 v60, v28, v4
	v_mul_f32_e32 v61, v29, v5
	v_mul_f32_e32 v82, v12, v4
	v_mul_f32_e32 v83, v13, v5
	v_mul_f32_e32 v62, v62, v6
	v_mul_f32_e32 v63, v63, v7
	v_mul_f32_e32 v65, v65, v9
	v_mul_f32_e32 v46, v46, v6
	v_mul_f32_e32 v47, v47, v7
	v_mul_f32_e32 v49, v49, v9
	v_mul_f32_e32 v84, v30, v6
	v_mul_f32_e32 v85, v31, v7
	v_mul_f32_e32 v87, v33, v9
	v_mul_f32_e32 v88, v14, v6
	v_mul_f32_e32 v89, v15, v7
	v_mul_f32_e32 v91, v17, v9
	v_lshl_add_u64 v[4:5], s[0:1], 0, v[0:1]
	v_and_b32_e32 v102, 1, v229
	v_mul_u32_u24_e32 v102, 0x7fe, v102
	v_mov_b32_e32 v103, 0
	v_lshl_add_u64 v[4:5], v[4:5], 0, v[102:103]
	s_mov_b32 vcc_lo, 0xaaaaaaaa
	s_mov_b32 vcc_hi, 0xaaaaaaaa
	v_lshlrev_b64 v[6:7], 11, v[2:3]
	v_ashrrev_i32_e32 v9, 31, v8
	v_or_b32_e32 v10, 2, v2
	v_lshl_add_u64 v[6:7], v[4:5], 0, v[6:7]
	v_lshlrev_b64 v[8:9], 11, v[8:9]
	v_ashrrev_i32_e32 v11, 31, v10
	v_or_b32_e32 v12, 3, v2
	v_mov_b32_dpp v98, v50 quad_perm:[1,0,3,2] row_mask:0xf bank_mask:0xf
	v_mov_b32_dpp v99, v51 quad_perm:[1,0,3,2] row_mask:0xf bank_mask:0xf
	v_cndmask_b32_e32 v100, v50, v99, vcc
	v_cndmask_b32_e32 v101, v98, v51, vcc
	v_cvt_pk_bf16_f32 v0, v100, v101
	v_lshl_add_u64 v[8:9], v[4:5], 0, v[8:9]
	v_lshlrev_b64 v[10:11], 11, v[10:11]
	v_ashrrev_i32_e32 v13, 31, v12
	v_or_b32_e32 v14, 8, v2
	global_store_dword v[6:7], v0, off
	v_lshl_add_u64 v[10:11], v[4:5], 0, v[10:11]
	v_lshlrev_b64 v[12:13], 11, v[12:13]
	v_ashrrev_i32_e32 v15, 31, v14
	v_mov_b32_dpp v98, v52 quad_perm:[1,0,3,2] row_mask:0xf bank_mask:0xf
	v_mov_b32_dpp v99, v53 quad_perm:[1,0,3,2] row_mask:0xf bank_mask:0xf
	v_cndmask_b32_e32 v100, v52, v99, vcc
	v_cndmask_b32_e32 v101, v98, v53, vcc
	v_cvt_pk_bf16_f32 v0, v100, v101
	v_lshl_add_u64 v[12:13], v[4:5], 0, v[12:13]
	v_lshlrev_b64 v[14:15], 11, v[14:15]
	v_or_b32_e32 v16, 9, v2
	global_store_dword v[10:11], v0, off
	v_mov_b32_e32 v104, v18
	v_lshl_add_u64 v[14:15], v[4:5], 0, v[14:15]
	v_ashrrev_i32_e32 v17, 31, v16
	v_or_b32_e32 v18, 10, v2
	v_mov_b32_dpp v98, v104 quad_perm:[1,0,3,2] row_mask:0xf bank_mask:0xf
	v_mov_b32_dpp v99, v19 quad_perm:[1,0,3,2] row_mask:0xf bank_mask:0xf
	v_cndmask_b32_e32 v100, v104, v99, vcc
	v_cndmask_b32_e32 v101, v98, v19, vcc
	v_cvt_pk_bf16_f32 v0, v100, v101
	v_lshlrev_b64 v[16:17], 11, v[16:17]
	v_ashrrev_i32_e32 v19, 31, v18
	v_lshl_add_u64 v[16:17], v[4:5], 0, v[16:17]
	v_lshlrev_b64 v[18:19], 11, v[18:19]
	global_store_dword v[14:15], v0, off
	v_mov_b32_e32 v104, v20
	v_lshl_add_u64 v[18:19], v[4:5], 0, v[18:19]
	v_or_b32_e32 v20, 11, v2
	v_mov_b32_dpp v98, v104 quad_perm:[1,0,3,2] row_mask:0xf bank_mask:0xf
	v_mov_b32_dpp v99, v21 quad_perm:[1,0,3,2] row_mask:0xf bank_mask:0xf
	v_cndmask_b32_e32 v100, v104, v99, vcc
	v_cndmask_b32_e32 v101, v98, v21, vcc
	v_cvt_pk_bf16_f32 v0, v100, v101
	v_ashrrev_i32_e32 v21, 31, v20
	v_lshlrev_b64 v[20:21], 11, v[20:21]
	v_lshl_add_u64 v[20:21], v[4:5], 0, v[20:21]
	v_or_b32_e32 v22, 16, v2
	global_store_dword v[18:19], v0, off
	v_mov_b32_e32 v104, v23
	v_ashrrev_i32_e32 v23, 31, v22
	v_lshlrev_b64 v[22:23], 11, v[22:23]
	v_lshl_add_u64 v[22:23], v[4:5], 0, v[22:23]
	v_or_b32_e32 v24, 17, v2
	v_mov_b32_dpp v98, v104 quad_perm:[1,0,3,2] row_mask:0xf bank_mask:0xf
	v_mov_b32_dpp v99, v25 quad_perm:[1,0,3,2] row_mask:0xf bank_mask:0xf
	v_cndmask_b32_e32 v100, v104, v99, vcc
	v_cndmask_b32_e32 v101, v98, v25, vcc
	v_cvt_pk_bf16_f32 v0, v100, v101
	v_ashrrev_i32_e32 v25, 31, v24
	v_or_b32_e32 v26, 18, v2
	v_lshlrev_b64 v[24:25], 11, v[24:25]
	v_ashrrev_i32_e32 v27, 31, v26
	v_or_b32_e32 v28, 19, v2
; __device__ __forceinline__ unsigned cvtpk(float lo, float hi) { f32x2_t v = {lo, hi}; bf16x2_t b = __builtin_convertvector(v, bf16x2_t); return __builtin_bit_cast(unsigned, b); }
; __device__ __forceinline__ int crowc(int r) { return (r & 3) + 8 * (r >> 2); }
; template <int DV>
; __device__ __forceinline__ void attn_store(const f32x16 (&o)[DV / 32], bf16_t* Op, int ldo) {
;     ...
; #pragma unroll
;     for (int dt = 0; dt < DV / 32; ++dt)
; #pragma unroll
;         for (int r = 0; r < 16; ++r) { const int row = 32 * wid + crowc(r) + 4 * hi; Op[(size_t)row * ldo + dt * 32 + r32] = (bf16_t)(cvtpk(o[dt][r], 0.f) & 0xffffu); }
	v_lshl_add_u64 v[24:25], v[4:5], 0, v[24:25]
	v_lshlrev_b64 v[26:27], 11, v[26:27]
	v_ashrrev_i32_e32 v29, 31, v28
	v_or_b32_e32 v30, 24, v2
	global_store_dword v[22:23], v0, off
	v_lshl_add_u64 v[26:27], v[4:5], 0, v[26:27]
	v_lshlrev_b64 v[28:29], 11, v[28:29]
	v_ashrrev_i32_e32 v31, 31, v30
	v_or_b32_e32 v32, 25, v2
	v_mov_b32_dpp v98, v34 quad_perm:[1,0,3,2] row_mask:0xf bank_mask:0xf
	v_mov_b32_dpp v99, v35 quad_perm:[1,0,3,2] row_mask:0xf bank_mask:0xf
	v_cndmask_b32_e32 v100, v34, v99, vcc
	v_cndmask_b32_e32 v101, v98, v35, vcc
	v_cvt_pk_bf16_f32 v0, v100, v101
	v_lshl_add_u64 v[28:29], v[4:5], 0, v[28:29]
	v_lshlrev_b64 v[30:31], 11, v[30:31]
	v_ashrrev_i32_e32 v33, 31, v32
	v_or_b32_e32 v34, 26, v2
	global_store_dword v[26:27], v0, off
	v_lshl_add_u64 v[30:31], v[4:5], 0, v[30:31]
	v_lshlrev_b64 v[32:33], 11, v[32:33]
	v_ashrrev_i32_e32 v35, 31, v34
	v_or_b32_e32 v2, 27, v2
	v_mov_b32_dpp v98, v62 quad_perm:[1,0,3,2] row_mask:0xf bank_mask:0xf
	v_mov_b32_dpp v99, v63 quad_perm:[1,0,3,2] row_mask:0xf bank_mask:0xf
	v_cndmask_b32_e32 v100, v62, v99, vcc
	v_cndmask_b32_e32 v101, v98, v63, vcc
	v_cvt_pk_bf16_f32 v0, v100, v101
	v_lshl_add_u64 v[32:33], v[4:5], 0, v[32:33]
	v_lshlrev_b64 v[34:35], 11, v[34:35]
	v_ashrrev_i32_e32 v3, 31, v2
	global_store_dword v[30:31], v0, off
	v_lshl_add_u64 v[34:35], v[4:5], 0, v[34:35]
	v_lshlrev_b64 v[2:3], 11, v[2:3]
	v_mov_b32_dpp v98, v64 quad_perm:[1,0,3,2] row_mask:0xf bank_mask:0xf
	v_mov_b32_dpp v99, v65 quad_perm:[1,0,3,2] row_mask:0xf bank_mask:0xf
	v_cndmask_b32_e32 v100, v64, v99, vcc
	v_cndmask_b32_e32 v101, v98, v65, vcc
	v_cvt_pk_bf16_f32 v0, v100, v101
	v_lshl_add_u64 v[2:3], v[4:5], 0, v[2:3]
	global_store_dword v[34:35], v0, off
	v_mov_b32_dpp v98, v74 quad_perm:[1,0,3,2] row_mask:0xf bank_mask:0xf
	v_mov_b32_dpp v99, v75 quad_perm:[1,0,3,2] row_mask:0xf bank_mask:0xf
	v_cndmask_b32_e32 v100, v74, v99, vcc
	v_cndmask_b32_e32 v101, v98, v75, vcc
	v_cvt_pk_bf16_f32 v0, v100, v101
	global_store_dword v[6:7], v0, off offset:64
	v_mov_b32_dpp v98, v36 quad_perm:[1,0,3,2] row_mask:0xf bank_mask:0xf
	v_mov_b32_dpp v99, v37 quad_perm:[1,0,3,2] row_mask:0xf bank_mask:0xf
	v_cndmask_b32_e32 v100, v36, v99, vcc
	v_cndmask_b32_e32 v101, v98, v37, vcc
	v_cvt_pk_bf16_f32 v0, v100, v101
	global_store_dword v[10:11], v0, off offset:64
	v_mov_b32_dpp v98, v38 quad_perm:[1,0,3,2] row_mask:0xf bank_mask:0xf
	v_mov_b32_dpp v99, v39 quad_perm:[1,0,3,2] row_mask:0xf bank_mask:0xf
	v_cndmask_b32_e32 v100, v38, v99, vcc
	v_cndmask_b32_e32 v101, v98, v39, vcc
	v_cvt_pk_bf16_f32 v0, v100, v101
	global_store_dword v[14:15], v0, off offset:64
	v_mov_b32_dpp v98, v40 quad_perm:[1,0,3,2] row_mask:0xf bank_mask:0xf
	v_mov_b32_dpp v99, v41 quad_perm:[1,0,3,2] row_mask:0xf bank_mask:0xf
	v_cndmask_b32_e32 v100, v40, v99, vcc
	v_cndmask_b32_e32 v101, v98, v41, vcc
	v_cvt_pk_bf16_f32 v0, v100, v101
	global_store_dword v[18:19], v0, off offset:64
	v_mov_b32_dpp v98, v42 quad_perm:[1,0,3,2] row_mask:0xf bank_mask:0xf
	v_mov_b32_dpp v99, v43 quad_perm:[1,0,3,2] row_mask:0xf bank_mask:0xf
	v_cndmask_b32_e32 v100, v42, v99, vcc
	v_cndmask_b32_e32 v101, v98, v43, vcc
	v_cvt_pk_bf16_f32 v0, v100, v101
	global_store_dword v[22:23], v0, off offset:64
	v_mov_b32_dpp v98, v44 quad_perm:[1,0,3,2] row_mask:0xf bank_mask:0xf
	v_mov_b32_dpp v99, v45 quad_perm:[1,0,3,2] row_mask:0xf bank_mask:0xf
	v_cndmask_b32_e32 v100, v44, v99, vcc
	v_cndmask_b32_e32 v101, v98, v45, vcc
	v_cvt_pk_bf16_f32 v0, v100, v101
	global_store_dword v[26:27], v0, off offset:64
	v_mov_b32_dpp v98, v46 quad_perm:[1,0,3,2] row_mask:0xf bank_mask:0xf
	v_mov_b32_dpp v99, v47 quad_perm:[1,0,3,2] row_mask:0xf bank_mask:0xf
	v_cndmask_b32_e32 v100, v46, v99, vcc
	v_cndmask_b32_e32 v101, v98, v47, vcc
	v_cvt_pk_bf16_f32 v0, v100, v101
	global_store_dword v[30:31], v0, off offset:64
	v_mov_b32_dpp v98, v48 quad_perm:[1,0,3,2] row_mask:0xf bank_mask:0xf
	v_mov_b32_dpp v99, v49 quad_perm:[1,0,3,2] row_mask:0xf bank_mask:0xf
	v_cndmask_b32_e32 v100, v48, v99, vcc
	v_cndmask_b32_e32 v101, v98, v49, vcc
	v_cvt_pk_bf16_f32 v0, v100, v101
	global_store_dword v[34:35], v0, off offset:64
	v_mov_b32_dpp v98, v76 quad_perm:[1,0,3,2] row_mask:0xf bank_mask:0xf
	v_mov_b32_dpp v99, v77 quad_perm:[1,0,3,2] row_mask:0xf bank_mask:0xf
	v_cndmask_b32_e32 v100, v76, v99, vcc
	v_cndmask_b32_e32 v101, v98, v77, vcc
	v_cvt_pk_bf16_f32 v0, v100, v101
	global_store_dword v[6:7], v0, off offset:128
	v_mov_b32_dpp v98, v78 quad_perm:[1,0,3,2] row_mask:0xf bank_mask:0xf
; __device__ __forceinline__ unsigned cvtpk(float lo, float hi) { f32x2_t v = {lo, hi}; bf16x2_t b = __builtin_convertvector(v, bf16x2_t); return __builtin_bit_cast(unsigned, b); }
; __device__ __forceinline__ int crowc(int r) { return (r & 3) + 8 * (r >> 2); }
; template <int DV>
; __device__ __forceinline__ void attn_store(const f32x16 (&o)[DV / 32], bf16_t* Op, int ldo) {
;     ...
; #pragma unroll
;     for (int dt = 0; dt < DV / 32; ++dt)
; #pragma unroll
;         for (int r = 0; r < 16; ++r) { const int row = 32 * wid + crowc(r) + 4 * hi; Op[(size_t)row * ldo + dt * 32 + r32] = (bf16_t)(cvtpk(o[dt][r], 0.f) & 0xffffu); }
; __global__ void __launch_bounds__(512, 2) fwd_kernel(Args a) {
;     ...
;         for (int it = cb_; it < 2048; it += G) { const int xcd_ = it & 7, jj_ = ((it >> 3) & 31) * 8 + (it >> 8); const int qb = jj_ & 15, rest = xcd_ * 16 + (jj_ >> 4);     unitM(lds, QM, MEMK, MEMVT, MIX, l, rest >> 3, (rest >> 1) & 3, rest & 1, qb); }
	v_mov_b32_dpp v99, v79 quad_perm:[1,0,3,2] row_mask:0xf bank_mask:0xf
	v_cndmask_b32_e32 v100, v78, v99, vcc
	v_cndmask_b32_e32 v101, v98, v79, vcc
	v_cvt_pk_bf16_f32 v0, v100, v101
	global_store_dword v[10:11], v0, off offset:128
	v_mov_b32_dpp v98, v54 quad_perm:[1,0,3,2] row_mask:0xf bank_mask:0xf
	v_mov_b32_dpp v99, v55 quad_perm:[1,0,3,2] row_mask:0xf bank_mask:0xf
	v_cndmask_b32_e32 v100, v54, v99, vcc
	v_cndmask_b32_e32 v101, v98, v55, vcc
	v_cvt_pk_bf16_f32 v0, v100, v101
	global_store_dword v[14:15], v0, off offset:128
	v_mov_b32_dpp v98, v56 quad_perm:[1,0,3,2] row_mask:0xf bank_mask:0xf
	v_mov_b32_dpp v99, v57 quad_perm:[1,0,3,2] row_mask:0xf bank_mask:0xf
	v_cndmask_b32_e32 v100, v56, v99, vcc
	v_cndmask_b32_e32 v101, v98, v57, vcc
	v_cvt_pk_bf16_f32 v0, v100, v101
	global_store_dword v[18:19], v0, off offset:128
	v_mov_b32_dpp v98, v58 quad_perm:[1,0,3,2] row_mask:0xf bank_mask:0xf
	v_mov_b32_dpp v99, v59 quad_perm:[1,0,3,2] row_mask:0xf bank_mask:0xf
	v_cndmask_b32_e32 v100, v58, v99, vcc
	v_cndmask_b32_e32 v101, v98, v59, vcc
	v_cvt_pk_bf16_f32 v0, v100, v101
	global_store_dword v[22:23], v0, off offset:128
	v_mov_b32_dpp v98, v60 quad_perm:[1,0,3,2] row_mask:0xf bank_mask:0xf
	v_mov_b32_dpp v99, v61 quad_perm:[1,0,3,2] row_mask:0xf bank_mask:0xf
	v_cndmask_b32_e32 v100, v60, v99, vcc
	v_cndmask_b32_e32 v101, v98, v61, vcc
	v_cvt_pk_bf16_f32 v0, v100, v101
	global_store_dword v[26:27], v0, off offset:128
	v_mov_b32_dpp v98, v84 quad_perm:[1,0,3,2] row_mask:0xf bank_mask:0xf
	v_mov_b32_dpp v99, v85 quad_perm:[1,0,3,2] row_mask:0xf bank_mask:0xf
	v_cndmask_b32_e32 v100, v84, v99, vcc
	v_cndmask_b32_e32 v101, v98, v85, vcc
	v_cvt_pk_bf16_f32 v0, v100, v101
	global_store_dword v[30:31], v0, off offset:128
	v_mov_b32_dpp v98, v86 quad_perm:[1,0,3,2] row_mask:0xf bank_mask:0xf
	v_mov_b32_dpp v99, v87 quad_perm:[1,0,3,2] row_mask:0xf bank_mask:0xf
	v_cndmask_b32_e32 v100, v86, v99, vcc
	v_cndmask_b32_e32 v101, v98, v87, vcc
	v_cvt_pk_bf16_f32 v0, v100, v101
	global_store_dword v[34:35], v0, off offset:128
	v_mov_b32_dpp v98, v66 quad_perm:[1,0,3,2] row_mask:0xf bank_mask:0xf
	v_mov_b32_dpp v99, v67 quad_perm:[1,0,3,2] row_mask:0xf bank_mask:0xf
	v_cndmask_b32_e32 v100, v66, v99, vcc
	v_cndmask_b32_e32 v101, v98, v67, vcc
	v_cvt_pk_bf16_f32 v0, v100, v101
	global_store_dword v[6:7], v0, off offset:192
	v_mov_b32_dpp v98, v68 quad_perm:[1,0,3,2] row_mask:0xf bank_mask:0xf
	v_mov_b32_dpp v99, v69 quad_perm:[1,0,3,2] row_mask:0xf bank_mask:0xf
	v_cndmask_b32_e32 v100, v68, v99, vcc
	v_cndmask_b32_e32 v101, v98, v69, vcc
	v_cvt_pk_bf16_f32 v0, v100, v101
	global_store_dword v[10:11], v0, off offset:192
	v_mov_b32_dpp v98, v70 quad_perm:[1,0,3,2] row_mask:0xf bank_mask:0xf
	v_mov_b32_dpp v99, v71 quad_perm:[1,0,3,2] row_mask:0xf bank_mask:0xf
	v_cndmask_b32_e32 v100, v70, v99, vcc
	v_cndmask_b32_e32 v101, v98, v71, vcc
	v_cvt_pk_bf16_f32 v0, v100, v101
	global_store_dword v[14:15], v0, off offset:192
	v_mov_b32_dpp v98, v72 quad_perm:[1,0,3,2] row_mask:0xf bank_mask:0xf
	v_mov_b32_dpp v99, v73 quad_perm:[1,0,3,2] row_mask:0xf bank_mask:0xf
	v_cndmask_b32_e32 v100, v72, v99, vcc
	v_cndmask_b32_e32 v101, v98, v73, vcc
	v_cvt_pk_bf16_f32 v0, v100, v101
	global_store_dword v[18:19], v0, off offset:192
	v_mov_b32_dpp v98, v80 quad_perm:[1,0,3,2] row_mask:0xf bank_mask:0xf
	v_mov_b32_dpp v99, v81 quad_perm:[1,0,3,2] row_mask:0xf bank_mask:0xf
	v_cndmask_b32_e32 v100, v80, v99, vcc
	v_cndmask_b32_e32 v101, v98, v81, vcc
	v_cvt_pk_bf16_f32 v0, v100, v101
	global_store_dword v[22:23], v0, off offset:192
	v_mov_b32_dpp v98, v82 quad_perm:[1,0,3,2] row_mask:0xf bank_mask:0xf
	v_mov_b32_dpp v99, v83 quad_perm:[1,0,3,2] row_mask:0xf bank_mask:0xf
	v_cndmask_b32_e32 v100, v82, v99, vcc
	v_cndmask_b32_e32 v101, v98, v83, vcc
	v_cvt_pk_bf16_f32 v0, v100, v101
	global_store_dword v[26:27], v0, off offset:192
	v_mov_b32_dpp v98, v88 quad_perm:[1,0,3,2] row_mask:0xf bank_mask:0xf
	v_mov_b32_dpp v99, v89 quad_perm:[1,0,3,2] row_mask:0xf bank_mask:0xf
	v_cndmask_b32_e32 v100, v88, v99, vcc
	v_cndmask_b32_e32 v101, v98, v89, vcc
	v_cvt_pk_bf16_f32 v0, v100, v101
	global_store_dword v[30:31], v0, off offset:192
	s_add_i32 s62, s62, s34
	v_mov_b32_dpp v98, v90 quad_perm:[1,0,3,2] row_mask:0xf bank_mask:0xf
	v_mov_b32_dpp v99, v91 quad_perm:[1,0,3,2] row_mask:0xf bank_mask:0xf
	v_cndmask_b32_e32 v100, v90, v99, vcc
	v_cndmask_b32_e32 v101, v98, v91, vcc
	v_cvt_pk_bf16_f32 v0, v100, v101
	s_cmpk_gt_i32 s62, 0x7ff
	global_store_dword v[34:35], v0, off offset:192
	s_cbranch_scc1 .LBB0_1198
